# v18 + in-projection epilogue operands (bias quads, row statistics) prefetched at the tile header into registers free through the K-loop
# speedup vs baseline: 1.1664x; 1.0003x over previous
; #define GASP __attribute__((address_space(1)))
;     __host__ __device__ bool next(int i, Unit& u) const {
;         const long L = (long)i * G + c; if (L >= nwg) return false;
;         int wgid = (int)L; { const int q = nwg / NXCD, r = nwg % NXCD, xcd = wgid % NXCD, off = wgid / NXCD; wgid = (xcd < r ? xcd * (q + 1) : r * (q + 1) + (xcd - r) * q) + off; }
;         const int nig = WGM * nN, gid = wgid / nig, fm = gid * WGM, gsz = (nM - fm) < WGM ? (nM - fm) : WGM;
;         u.pm = fm + ((wgid % nig) % gsz); u.pn = (wgid % nig) / gsz; return true;
;     __device__ __forceinline__ void operator()(const f32x4 (&acc_)[2][2][4][2], const Unit& u, int wr, int wc, int fr, int fq) const {
;     ...
;         { const GASP float* ssp = (const GASP float*)(w + WS_SS) + (l & 1) * 32768 + u.pm * BM + wr * 64 + fr; const float* bp = (const float*)(w + WS_BIAS) + ((size_t)l * 8 + (u.pm >> 4)) * 6144 + u.pn * BM + 32 * wc + 8 * fq;
;           f32x4 bs[2][2];
; _Pragma("unroll") for (int bj = 0; bj < 2; ++bj) _Pragma("unroll") for (int n = 0; n < 2; ++n) bs[bj][n] = *(const GASP f32x4*)(bp + bj * HALF + 4 * n);
;           float sv[2][4];
; _Pragma("unroll") for (int ai = 0; ai < 2; ++ai) _Pragma("unroll") for (int m = 0; m < 4; ++m) sv[ai][m] = ssp[ai * HALF + m * 16];
.LBB0_172:
	s_ashr_i32 s72, s26, 4
	s_add_i32 s72, s72, s56
	s_mulk_i32 s72, 0x6000
	s_lshl_b32 s73, s42, 10
	s_add_i32 s72, s72, s73
	s_lshl_b32 s73, s50, 7
	s_add_i32 s72, s72, s73
	s_add_u32 s72, s72, 0x35a00000
	s_add_u32 s74, s0, s72
	s_addc_u32 s75, s1, 0
	v_lshlrev_b32_e32 v237, 5, v224
	global_load_dwordx4 v[238:241], v237, s[74:75]
	global_load_dwordx4 v[242:245], v237, s[74:75] offset:16
	global_load_dwordx4 v[246:249], v237, s[74:75] offset:512
	global_load_dwordx4 v[250:253], v237, s[74:75] offset:528
	s_lshl_b32 s72, s26, 10
	s_lshl_b32 s73, s36, 8
	s_add_i32 s72, s72, s73
	s_add_i32 s72, s72, s58
	s_add_u32 s72, s72, 0x900000
	s_add_u32 s68, s0, s72
	s_addc_u32 s69, s1, 0
	v_lshlrev_b32_e32 v234, 2, v193
	global_load_dword v192, v234, s[68:69]
	global_load_dword v204, v234, s[68:69] offset:64
	global_load_dword v210, v234, s[68:69] offset:128
	global_load_dword v211, v234, s[68:69] offset:192
	global_load_dword v222, v234, s[68:69] offset:512
	global_load_dword v223, v234, s[68:69] offset:576
	global_load_dword v227, v234, s[68:69] offset:640
	global_load_dword v228, v234, s[68:69] offset:704
	s_add_i32 s57, s57, 1
	s_mul_i32 s4, s57, s3
	s_mul_hi_u32 s5, s57, s44
	s_add_i32 s5, s5, s4
	s_mul_i32 s4, s57, s44
	s_add_u32 s18, s4, s2
	s_addc_u32 s19, s5, s45
	v_mov_b64_e32 v[0:1], 0xc00
	v_cmp_lt_i64_e64 s[4:5], s[18:19], v[0:1]
	v_mov_b64_e32 v[0:1], 0xbff
	v_cmp_gt_i64_e32 vcc, s[18:19], v[0:1]
	s_cbranch_vccnz .LBB0_174
	s_ashr_i32 s14, s18, 31
	s_lshr_b32 s14, s14, 29
	s_add_i32 s14, s18, s14
	s_ashr_i32 s15, s14, 3
	s_and_b32 s14, s14, -8
	s_sub_i32 s14, s18, s14
	s_cmp_lt_i32 s14, 0
	s_movk_i32 s16, 0x181
	s_cselect_b32 s16, s16, 0x180
	s_mul_i32 s14, s14, s16
	s_add_i32 s14, s14, s15
	s_mul_hi_i32 s15, s14, 0x2aaaaaab
	s_lshr_b32 s16, s15, 31
	s_ashr_i32 s15, s15, 5
	s_add_i32 s15, s15, s16
	s_lshl_b32 s16, s15, 3
	s_sub_i32 s17, 0x80, s16
	s_min_i32 s17, s17, 8
	s_abs_i32 s18, s17
	v_cvt_f32_u32_e32 v0, s18
	s_sub_i32 s20, 0, s18
	s_mulk_i32 s15, 0xc0
	s_sub_i32 s15, s14, s15
	v_rcp_iflag_f32_e32 v0, v0
	s_abs_i32 s14, s15
	s_xor_b32 s19, s15, s17
	s_ashr_i32 s19, s19, 31
	v_mul_f32_e32 v0, 0x4f7ffffe, v0
	v_cvt_u32_f32_e32 v0, v0
	s_nop 0
	v_readfirstlane_b32 s21, v0
	s_mul_i32 s20, s20, s21
	s_mul_hi_u32 s20, s21, s20
	s_add_i32 s21, s21, s20
	s_mul_hi_u32 s20, s14, s21
	s_mul_i32 s21, s20, s18
	s_sub_i32 s14, s14, s21
	s_add_i32 s24, s20, 1
	s_sub_i32 s21, s14, s18
	s_cmp_ge_u32 s14, s18
	s_cselect_b32 s20, s24, s20
	s_cselect_b32 s14, s21, s14
	s_add_i32 s21, s20, 1
	s_cmp_ge_u32 s14, s18
	s_cselect_b32 s14, s21, s20
	s_xor_b32 s14, s14, s19
	s_sub_i32 s14, s14, s19
	s_mul_i32 s17, s14, s17
	s_sub_i32 s15, s15, s17
	s_add_i32 s16, s16, s15

; #define GASP __attribute__((address_space(1)))
;     __device__ __forceinline__ void operator()(const f32x4 (&acc_)[2][2][4][2], const Unit& u, int wr, int wc, int fr, int fq) const {
;     ...
;         { const GASP float* ssp = (const GASP float*)(w + WS_SS) + (l & 1) * 32768 + u.pm * BM + wr * 64 + fr; const float* bp = (const float*)(w + WS_BIAS) + ((size_t)l * 8 + (u.pm >> 4)) * 6144 + u.pn * BM + 32 * wc + 8 * fq;
;           f32x4 bs[2][2];
; _Pragma("unroll") for (int bj = 0; bj < 2; ++bj) _Pragma("unroll") for (int n = 0; n < 2; ++n) bs[bj][n] = *(const GASP f32x4*)(bp + bj * HALF + 4 * n);
;           float sv[2][4];
; _Pragma("unroll") for (int ai = 0; ai < 2; ++ai) _Pragma("unroll") for (int m = 0; m < 4; ++m) sv[ai][m] = ssp[ai * HALF + m * 16];
;           asm volatile("" : "+v"(sv[0][0]), "+v"(sv[0][1]), "+v"(sv[0][2]), "+v"(sv[0][3]), "+v"(sv[1][0]), "+v"(sv[1][1]), "+v"(sv[1][2]), "+v"(sv[1][3]));
.LBB0_178:
	v_mov_b32_e32 v128, v224
	s_mov_b32 s17, s36
	v_mov_b32_e32 v144, v193
	s_mov_b32 s15, s50
	s_lshl_b32 s6, s26, 8
	s_lshl_b32 s28, s17, 6
	s_ashr_i32 s17, s26, 4
	s_ashr_i32 s7, s6, 31
	s_ashr_i32 s29, s28, 31
	s_ashr_i32 s24, s17, 31
	s_add_u32 s17, s17, s56
	s_addc_u32 s24, s24, 0
	s_mulk_i32 s24, 0x6000
	s_mul_hi_u32 s25, s17, 0x6000
	s_mov_b64 s[22:23], s[0:1]
	s_add_i32 s25, s25, s24
	s_mulk_i32 s17, 0x6000
	s_add_u32 s17, s22, s17
	s_addc_u32 s43, s23, s25
	s_lshl_b32 s24, s42, 8
	s_ashr_i32 s25, s24, 31
	s_lshl_b64 s[26:27], s[24:25], 2
	s_add_u32 s17, s17, s26
	s_addc_u32 s25, s43, s27
	s_lshl_b32 s26, s15, 5
	s_ashr_i32 s27, s26, 31
	s_lshl_b64 s[60:61], s[26:27], 2
	s_add_u32 s60, s17, s60
	v_lshlrev_b32_e32 v188, 3, v128
	s_addc_u32 s61, s25, s61
	v_ashrrev_i32_e32 v189, 31, v188
	v_lshl_add_u64 v[128:129], v[188:189], 2, s[60:61]
	s_mov_b64 s[60:61], 0x35a00000
	s_mov_b32 s17, 0x35a00000
	v_lshl_add_u64 v[132:133], v[128:129], 0, s[60:61]
	v_add_co_u32_e32 v128, vcc, s17, v128
	s_add_u32 s17, s22, s58
	s_addc_u32 s25, s23, 0
	s_lshl_b64 s[60:61], s[6:7], 2
	s_add_u32 s7, s17, s60
	s_addc_u32 s17, s25, s61
	s_lshl_b64 s[60:61], s[28:29], 2
	s_add_u32 s60, s7, s60
	v_ashrrev_i32_e32 v145, 31, v144
	s_addc_u32 s61, s17, s61
	v_addc_co_u32_e32 v129, vcc, 0, v129, vcc
	v_lshl_add_u64 v[146:147], v[144:145], 2, s[60:61]
	s_mov_b64 s[60:61], 0x900000
	s_mov_b32 s7, 0x900000
	v_lshl_add_u64 v[148:149], v[146:147], 0, s[60:61]
	v_add_co_u32_e32 v146, vcc, s7, v146
	v_mov_b32_e32 v140, v238
	v_mov_b32_e32 v141, v239
	v_mov_b32_e32 v142, v240
	v_mov_b32_e32 v143, v241
	v_mov_b32_e32 v136, v242
	v_mov_b32_e32 v137, v243
	v_mov_b32_e32 v138, v244
	v_mov_b32_e32 v139, v245
	s_nop 0
	v_mov_b32_e32 v128, v250
	v_mov_b32_e32 v129, v251
	v_mov_b32_e32 v130, v252
	v_mov_b32_e32 v131, v253
	s_nop 0
	v_mov_b32_e32 v132, v246
	v_mov_b32_e32 v133, v247
	v_mov_b32_e32 v134, v248
	v_mov_b32_e32 v135, v249
	v_addc_co_u32_e32 v147, vcc, 0, v147, vcc
	v_mov_b32_e32 v150, v192
	v_mov_b32_e32 v145, v228
	s_nop 0
	v_mov_b32_e32 v146, v227
	v_mov_b32_e32 v147, v223
	v_mov_b32_e32 v151, v222
	v_mov_b32_e32 v152, v211
	v_mov_b32_e32 v153, v210
	s_nop 0
	v_mov_b32_e32 v149, v204
	s_ashr_i32 s59, s42, 2
	s_and_b32 s17, s24, 0x300
	s_add_i32 s6, s28, s6
	s_and_b32 s25, s42, -8
	v_add_u32_e32 v190, s6, v144
	s_mov_b64 s[6:7], -1
	s_cmp_lg_u32 s25, 8
	s_waitcnt vmcnt(0)
;     __device__ __forceinline__ void operator()(const f32x4 (&acc_)[2][2][4][2], const Unit& u, int wr, int wc, int fr, int fq) const {
;     ...
; _Pragma("unroll") for (int ai = 0; ai < 2; ++ai) _Pragma("unroll") for (int m = 0; m < 4; ++m) { const float rr = __builtin_amdgcn_rsqf(sv[ai][m] * (1.f / 2048.f) + 1e-6f);
; _Pragma("unroll") for (int bj = 0; bj < 2; ++bj) _Pragma("unroll") for (int n = 0; n < 2; ++n) acc[ai][bj][m][n] = acc_[ai][bj][m][n] * rr + bs[bj][n]; } }
;     ...
;         const int seg = u.pn >> 2, colt = (u.pn & 3) * 256, row0 = u.pm * BM + wr * 64 + fr;
;         if (seg == 2 || seg == 3) {
	s_nop 0
	v_fmamk_f32 v148, v150, 0x3a000000, v231
	v_rsq_f32_e32 v148, v148
	v_fmamk_f32 v146, v146, 0x3a000000, v231
	v_rsq_f32_e32 v146, v146
	v_fmamk_f32 v147, v147, 0x3a000000, v231
	v_pk_fma_f32 v[122:123], v[122:123], v[148:149], v[142:143] op_sel_hi:[1,0,1]
	v_pk_fma_f32 v[120:121], v[120:121], v[148:149], v[140:141] op_sel_hi:[1,0,1]
	v_pk_fma_f32 v[114:115], v[114:115], v[148:149], v[138:139] op_sel_hi:[1,0,1]
	v_pk_fma_f32 v[112:113], v[112:113], v[148:149], v[136:137] op_sel_hi:[1,0,1]
	v_pk_fma_f32 v[126:127], v[126:127], v[148:149], v[134:135] op_sel_hi:[1,0,1]
	v_pk_fma_f32 v[124:125], v[124:125], v[148:149], v[132:133] op_sel_hi:[1,0,1]
	v_pk_fma_f32 v[118:119], v[118:119], v[148:149], v[130:131] op_sel_hi:[1,0,1]
	v_pk_fma_f32 v[116:117], v[116:117], v[148:149], v[128:129] op_sel_hi:[1,0,1]
	v_fmamk_f32 v148, v149, 0x3a000000, v231
	v_rsq_f32_e32 v148, v148
	v_fmamk_f32 v145, v145, 0x3a000000, v231
	v_pk_fma_f32 v[18:19], v[18:19], v[146:147], v[142:143] op_sel_hi:[1,0,1]
	v_pk_fma_f32 v[16:17], v[16:17], v[146:147], v[140:141] op_sel_hi:[1,0,1]
	v_pk_fma_f32 v[78:79], v[78:79], v[148:149], v[142:143] op_sel_hi:[1,0,1]
	v_pk_fma_f32 v[76:77], v[76:77], v[148:149], v[140:141] op_sel_hi:[1,0,1]
	v_pk_fma_f32 v[62:63], v[62:63], v[148:149], v[138:139] op_sel_hi:[1,0,1]
	v_pk_fma_f32 v[60:61], v[60:61], v[148:149], v[136:137] op_sel_hi:[1,0,1]
	v_pk_fma_f32 v[86:87], v[86:87], v[148:149], v[134:135] op_sel_hi:[1,0,1]
	v_pk_fma_f32 v[84:85], v[84:85], v[148:149], v[132:133] op_sel_hi:[1,0,1]
	v_pk_fma_f32 v[70:71], v[70:71], v[148:149], v[130:131] op_sel_hi:[1,0,1]
	v_pk_fma_f32 v[68:69], v[68:69], v[148:149], v[128:129] op_sel_hi:[1,0,1]
	v_fmamk_f32 v148, v153, 0x3a000000, v231
	v_rsq_f32_e32 v148, v148
	v_pk_fma_f32 v[22:23], v[22:23], v[146:147], v[138:139] op_sel_hi:[1,0,1]
	v_pk_fma_f32 v[20:21], v[20:21], v[146:147], v[136:137] op_sel_hi:[1,0,1]
	v_pk_fma_f32 v[58:59], v[58:59], v[146:147], v[134:135] op_sel_hi:[1,0,1]
	v_pk_fma_f32 v[54:55], v[54:55], v[148:149], v[142:143] op_sel_hi:[1,0,1]
	v_pk_fma_f32 v[52:53], v[52:53], v[148:149], v[140:141] op_sel_hi:[1,0,1]
	v_pk_fma_f32 v[38:39], v[38:39], v[148:149], v[138:139] op_sel_hi:[1,0,1]
	v_pk_fma_f32 v[36:37], v[36:37], v[148:149], v[136:137] op_sel_hi:[1,0,1]
	v_pk_fma_f32 v[66:67], v[66:67], v[148:149], v[134:135] op_sel_hi:[1,0,1]
	v_pk_fma_f32 v[64:65], v[64:65], v[148:149], v[132:133] op_sel_hi:[1,0,1]
	v_pk_fma_f32 v[50:51], v[50:51], v[148:149], v[130:131] op_sel_hi:[1,0,1]
	v_pk_fma_f32 v[48:49], v[48:49], v[148:149], v[128:129] op_sel_hi:[1,0,1]
	v_fmamk_f32 v148, v152, 0x3a000000, v231
	v_rsq_f32_e32 v148, v148
	v_pk_fma_f32 v[56:57], v[56:57], v[146:147], v[132:133] op_sel_hi:[1,0,1]
	v_pk_fma_f32 v[42:43], v[42:43], v[146:147], v[130:131] op_sel_hi:[1,0,1]
	v_pk_fma_f32 v[40:41], v[40:41], v[146:147], v[128:129] op_sel_hi:[1,0,1]
	v_pk_fma_f32 v[34:35], v[34:35], v[148:149], v[142:143] op_sel_hi:[1,0,1]
	v_pk_fma_f32 v[32:33], v[32:33], v[148:149], v[140:141] op_sel_hi:[1,0,1]
	v_pk_fma_f32 v[26:27], v[26:27], v[148:149], v[138:139] op_sel_hi:[1,0,1]
	v_pk_fma_f32 v[24:25], v[24:25], v[148:149], v[136:137] op_sel_hi:[1,0,1]
	v_pk_fma_f32 v[46:47], v[46:47], v[148:149], v[134:135] op_sel_hi:[1,0,1]
	v_pk_fma_f32 v[44:45], v[44:45], v[148:149], v[132:133] op_sel_hi:[1,0,1]
	v_pk_fma_f32 v[30:31], v[30:31], v[148:149], v[130:131] op_sel_hi:[1,0,1]
	v_pk_fma_f32 v[28:29], v[28:29], v[148:149], v[128:129] op_sel_hi:[1,0,1]
	v_fmamk_f32 v148, v151, 0x3a000000, v231
	v_rsq_f32_e32 v148, v148
	v_rsq_f32_e32 v146, v145
	v_pk_fma_f32 v[98:99], v[98:99], v[148:149], v[142:143] op_sel_hi:[1,0,1]
	v_pk_fma_f32 v[96:97], v[96:97], v[148:149], v[140:141] op_sel_hi:[1,0,1]
	v_pk_fma_f32 v[102:103], v[102:103], v[148:149], v[138:139] op_sel_hi:[1,0,1]
	v_pk_fma_f32 v[100:101], v[100:101], v[148:149], v[136:137] op_sel_hi:[1,0,1]
	v_pk_fma_f32 v[110:111], v[110:111], v[148:149], v[134:135] op_sel_hi:[1,0,1]
	v_pk_fma_f32 v[108:109], v[108:109], v[148:149], v[132:133] op_sel_hi:[1,0,1]
	v_pk_fma_f32 v[106:107], v[106:107], v[148:149], v[130:131] op_sel_hi:[1,0,1]
	v_pk_fma_f32 v[104:105], v[104:105], v[148:149], v[128:129] op_sel_hi:[1,0,1]
	v_rsq_f32_e32 v148, v147
	v_pk_fma_f32 v[2:3], v[2:3], v[146:147], v[142:143] op_sel_hi:[1,0,1]
	v_pk_fma_f32 v[0:1], v[0:1], v[146:147], v[140:141] op_sel_hi:[1,0,1]
	v_pk_fma_f32 v[6:7], v[6:7], v[146:147], v[138:139] op_sel_hi:[1,0,1]
	v_pk_fma_f32 v[74:75], v[74:75], v[148:149], v[142:143] op_sel_hi:[1,0,1]
	v_pk_fma_f32 v[72:73], v[72:73], v[148:149], v[140:141] op_sel_hi:[1,0,1]
	v_pk_fma_f32 v[82:83], v[82:83], v[148:149], v[138:139] op_sel_hi:[1,0,1]
	v_pk_fma_f32 v[80:81], v[80:81], v[148:149], v[136:137] op_sel_hi:[1,0,1]
	v_pk_fma_f32 v[94:95], v[94:95], v[148:149], v[134:135] op_sel_hi:[1,0,1]
	v_pk_fma_f32 v[92:93], v[92:93], v[148:149], v[132:133] op_sel_hi:[1,0,1]
	v_pk_fma_f32 v[90:91], v[90:91], v[148:149], v[130:131] op_sel_hi:[1,0,1]
	v_pk_fma_f32 v[88:89], v[88:89], v[148:149], v[128:129] op_sel_hi:[1,0,1]
	v_pk_fma_f32 v[4:5], v[4:5], v[146:147], v[136:137] op_sel_hi:[1,0,1]
	v_pk_fma_f32 v[10:11], v[10:11], v[146:147], v[134:135] op_sel_hi:[1,0,1]
	v_pk_fma_f32 v[8:9], v[8:9], v[146:147], v[132:133] op_sel_hi:[1,0,1]
	v_pk_fma_f32 v[14:15], v[14:15], v[146:147], v[130:131] op_sel_hi:[1,0,1]
	v_pk_fma_f32 v[12:13], v[12:13], v[146:147], v[128:129] op_sel_hi:[1,0,1]
	s_cbranch_scc1 .LBB0_181
	s_andn2_b64 vcc, exec, s[6:7]
	s_cbranch_vccz .LBB0_218
